# P11 q-tile set-up (dilation-1 and -4 passes): norm-gain and rope-row loads issued right behind the q-row loads instead of in two later groups
# baseline (speedup 1.0000x reference)
.LBB0_1501:
	s_or_b32 s0, s2, s81
	s_lshl_b32 s2, s0, 5
	v_or_b32_e32 v0, s2, v172
	v_add_u32_e32 v129, s80, v0
	v_add_u32_e32 v0, s73, v129
	v_lshl_add_u64 v[2:3], s[56:57], 0, v[0:1]
	v_mad_u64_u32 v[4:5], s[0:1], v2, s27, v[126:127]
	v_mad_i32_i24 v5, v3, s27, v5
	s_lshl_b32 s14, s79, 1
	v_lshl_add_u64 v[2:3], v[4:5], 0, s[14:15]
	v_lshl_add_u64 v[6:7], v[2:3], 0, v[130:131]
	v_add_co_u32_e32 v2, vcc, s83, v6
	s_mov_b64 s[0:1], 0xd000800
	s_nop 0
	v_addc_co_u32_e32 v3, vcc, 0, v7, vcc
	global_load_dwordx4 v[2:5], v[2:3], off offset:2048
	v_lshl_add_u64 v[14:15], v[6:7], 0, s[0:1]
	global_load_dwordx4 v[6:9], v[14:15], off offset:64
	global_load_dwordx4 v[10:13], v[14:15], off offset:32
	s_nop 0
	global_load_dwordx4 v[14:17], v[14:15], off offset:96
	v_lshlrev_b64 v[244:245], 8, v[0:1]
	v_lshl_add_u64 v[246:247], v[118:119], 0, v[244:245]
	global_load_dwordx4 v[174:177], v[120:121], off offset:64
	global_load_dwordx4 v[178:181], v[120:121], off offset:192
	global_load_dwordx4 v[182:185], v[120:121], off offset:80
	global_load_dwordx4 v[186:189], v[246:247], off offset:128
	global_load_dwordx4 v[190:193], v[246:247], off offset:144
	global_load_dwordx4 v[194:197], v[120:121], off offset:208
	global_load_dwordx4 v[198:201], v[120:121], off
	global_load_dwordx4 v[202:205], v[120:121], off offset:16
	global_load_dwordx4 v[206:209], v[120:121], off offset:128
	global_load_dwordx4 v[210:213], v[120:121], off offset:144
	global_load_dwordx4 v[214:217], v[246:247], off offset:160
	global_load_dwordx4 v[218:221], v[246:247], off offset:176
	global_load_dwordx4 v[222:225], v[246:247], off
	global_load_dwordx4 v[232:235], v[246:247], off offset:16
	global_load_dwordx4 v[236:239], v[246:247], off offset:32
	global_load_dwordx4 v[240:243], v[246:247], off offset:48
	s_or_b32 s33, s2, s73
	s_max_i32 s2, s33, 0x80
	s_add_i32 s96, s2, 0xffffff80
	s_cmp_gt_i32 s96, s33
	s_waitcnt vmcnt(18)
	v_lshlrev_b32_e32 v27, 16, v7
	v_lshlrev_b32_e32 v29, 16, v3
	v_lshlrev_b32_e32 v28, 16, v2
	v_and_b32_e32 v33, 0xffff0000, v3
	v_and_b32_e32 v32, 0xffff0000, v2
	v_lshlrev_b32_e32 v26, 16, v6
	v_and_b32_e32 v31, 0xffff0000, v7
	v_and_b32_e32 v30, 0xffff0000, v6
	v_lshlrev_b32_e32 v19, 16, v9
	v_lshlrev_b32_e32 v18, 16, v8
	v_and_b32_e32 v23, 0xffff0000, v9
	v_and_b32_e32 v22, 0xffff0000, v8
	s_waitcnt vmcnt(17)
	v_lshlrev_b32_e32 v7, 16, v11
	v_lshlrev_b32_e32 v6, 16, v10
	v_and_b32_e32 v9, 0xffff0000, v11
	v_and_b32_e32 v8, 0xffff0000, v10
	v_lshlrev_b32_e32 v3, 16, v13
	v_lshlrev_b32_e32 v2, 16, v12
	v_and_b32_e32 v39, 0xffff0000, v13
	v_and_b32_e32 v38, 0xffff0000, v12
	v_pk_mul_f32 v[10:11], v[28:29], v[28:29]
	v_pk_mul_f32 v[12:13], v[32:33], v[32:33]
	v_lshlrev_b32_e32 v21, 16, v5
	v_add_f32_e32 v10, v10, v12
	v_lshlrev_b32_e32 v20, 16, v4
	v_add_f32_e32 v10, v11, v10
	v_and_b32_e32 v25, 0xffff0000, v5
	v_and_b32_e32 v24, 0xffff0000, v4
	s_waitcnt vmcnt(16)
	v_lshlrev_b32_e32 v37, 16, v15
	v_lshlrev_b32_e32 v36, 16, v14
	v_and_b32_e32 v41, 0xffff0000, v15
	v_and_b32_e32 v40, 0xffff0000, v14
	v_pk_mul_f32 v[14:15], v[20:21], v[20:21]
	v_add_f32_e32 v10, v13, v10
	v_lshlrev_b32_e32 v5, 16, v17
	v_lshlrev_b32_e32 v4, 16, v16
	v_and_b32_e32 v35, 0xffff0000, v17
	v_and_b32_e32 v34, 0xffff0000, v16
	v_pk_mul_f32 v[16:17], v[24:25], v[24:25]
	v_add_f32_e32 v10, v14, v10
	v_add_f32_e32 v10, v16, v10
	v_add_f32_e32 v10, v15, v10
	v_pk_mul_f32 v[42:43], v[6:7], v[6:7]
	v_add_f32_e32 v10, v17, v10
	v_pk_mul_f32 v[44:45], v[8:9], v[8:9]
	v_add_f32_e32 v10, v42, v10
	v_add_f32_e32 v10, v44, v10
	v_add_f32_e32 v10, v43, v10
	v_pk_mul_f32 v[46:47], v[2:3], v[2:3]
	v_add_f32_e32 v10, v45, v10
	v_pk_mul_f32 v[48:49], v[38:39], v[38:39]
	v_add_f32_e32 v10, v46, v10
	v_add_f32_e32 v10, v48, v10
	v_add_f32_e32 v10, v47, v10
	v_pk_mul_f32 v[50:51], v[26:27], v[26:27]
	v_add_f32_e32 v10, v49, v10
	v_pk_mul_f32 v[52:53], v[30:31], v[30:31]
	v_add_f32_e32 v10, v50, v10
	v_add_f32_e32 v10, v52, v10
	v_add_f32_e32 v10, v51, v10
	v_pk_mul_f32 v[54:55], v[18:19], v[18:19]
	v_add_f32_e32 v10, v53, v10
	v_pk_mul_f32 v[56:57], v[22:23], v[22:23]
	v_add_f32_e32 v10, v54, v10
	v_add_f32_e32 v10, v56, v10
	v_add_f32_e32 v10, v55, v10
	v_pk_mul_f32 v[58:59], v[36:37], v[36:37]
	v_add_f32_e32 v10, v57, v10
	v_pk_mul_f32 v[60:61], v[40:41], v[40:41]
	v_add_f32_e32 v10, v58, v10
	v_add_f32_e32 v10, v60, v10
	v_add_f32_e32 v10, v59, v10
	v_pk_mul_f32 v[62:63], v[4:5], v[4:5]
	v_add_f32_e32 v10, v61, v10
	v_pk_mul_f32 v[64:65], v[34:35], v[34:35]
	v_add_f32_e32 v10, v62, v10
	v_add_f32_e32 v10, v64, v10
	v_add_f32_e32 v10, v63, v10
	v_add_f32_e32 v10, v65, v10
	ds_bpermute_b32 v11, v117, v10
	s_cbranch_scc1 .LBB0_1520
	s_waitcnt vmcnt(0)
	v_mov_b32_e32 v42, v174
	v_mov_b32_e32 v43, v175
	v_mov_b32_e32 v44, v176
	v_mov_b32_e32 v45, v177
	v_mov_b32_e32 v46, v178
	v_mov_b32_e32 v47, v179
	v_mov_b32_e32 v48, v180
	v_mov_b32_e32 v49, v181
	v_mov_b32_e32 v50, v182
	v_mov_b32_e32 v51, v183
	v_mov_b32_e32 v52, v184
	v_mov_b32_e32 v53, v185
	v_lshlrev_b64 v[12:13], 8, v[0:1]
	v_lshl_add_u64 v[94:95], v[118:119], 0, v[12:13]
	v_mov_b32_e32 v54, v186
	v_mov_b32_e32 v55, v187
	v_mov_b32_e32 v56, v188
	v_mov_b32_e32 v57, v189
	v_mov_b32_e32 v58, v190
	v_mov_b32_e32 v59, v191
	v_mov_b32_e32 v60, v192
	v_mov_b32_e32 v61, v193
	v_mov_b32_e32 v62, v194
	v_mov_b32_e32 v63, v195
	v_mov_b32_e32 v64, v196
	v_mov_b32_e32 v65, v197
	s_waitcnt lgkmcnt(0)
	v_add_f32_e32 v14, v10, v11
	v_mov_b32_e32 v66, v198
	v_mov_b32_e32 v67, v199
	v_mov_b32_e32 v68, v200
	v_mov_b32_e32 v69, v201
	v_mov_b32_e32 v70, v202
	v_mov_b32_e32 v71, v203
	v_mov_b32_e32 v72, v204
	v_mov_b32_e32 v73, v205
	v_mov_b32_e32 v74, v206
	v_mov_b32_e32 v75, v207
	v_mov_b32_e32 v76, v208
	v_mov_b32_e32 v77, v209
	v_mov_b32_e32 v10, v210
	v_mov_b32_e32 v11, v211
	v_mov_b32_e32 v12, v212
	v_mov_b32_e32 v13, v213
	v_mov_b32_e32 v78, v214
	v_mov_b32_e32 v79, v215
	v_mov_b32_e32 v80, v216
	v_mov_b32_e32 v81, v217
	v_mov_b32_e32 v82, v218
	v_mov_b32_e32 v83, v219
	v_mov_b32_e32 v84, v220
	v_mov_b32_e32 v85, v221
	v_fmamk_f32 v14, v14, 0x3c800000, v141
	v_mul_f32_e32 v15, 0x4f800000, v14
	v_cmp_gt_f32_e32 vcc, s87, v14
	v_mov_b32_e32 v86, v222
	v_mov_b32_e32 v87, v223
	v_mov_b32_e32 v88, v224
	v_mov_b32_e32 v89, v225
	v_mov_b32_e32 v90, v232
	v_mov_b32_e32 v91, v233
	v_mov_b32_e32 v92, v234
	v_mov_b32_e32 v93, v235
	v_cndmask_b32_e32 v14, v14, v15, vcc
	v_sqrt_f32_e32 v15, v14
	v_or_b32_e32 v0, s33, v172
	v_mov_b32_e32 v136, 0
	v_sub_u32_e32 v0, v0, v123
	v_add_u32_e32 v16, -1, v15
	v_add_u32_e32 v17, 1, v15
	v_fma_f32 v96, -v16, v15, v14
	v_fma_f32 v97, -v17, v15, v14
	v_cmp_ge_f32_e64 s[0:1], 0, v96
	s_add_i32 s3, s2, 0xffffffa0
	s_lshl_b32 s68, s96, 6
	v_cndmask_b32_e64 v15, v15, v16, s[0:1]
	v_cmp_lt_f32_e64 s[0:1], 0, v97
	s_add_i32 s59, s33, 0xffffffa0
	v_add_u32_e32 v137, -8, v0
	v_cndmask_b32_e64 v15, v15, v17, s[0:1]
	v_mul_f32_e32 v16, 0x37800000, v15
	v_cndmask_b32_e32 v15, v15, v16, vcc
	v_cmp_class_f32_e32 vcc, v14, v142
	v_add_u32_e32 v149, -9, v0
	v_add_u32_e32 v150, -10, v0
	v_cndmask_b32_e32 v98, v15, v14, vcc
	v_mov_b32_e32 v14, v236
	v_mov_b32_e32 v15, v237
	v_mov_b32_e32 v16, v238
	v_mov_b32_e32 v17, v239
	s_nop 0
	v_mov_b32_e32 v94, v240
	v_mov_b32_e32 v95, v241
	v_mov_b32_e32 v96, v242
	v_mov_b32_e32 v97, v243
	v_div_scale_f32 v99, s[0:1], v98, v98, s88
	v_rcp_f32_e32 v100, v99
	v_div_scale_f32 v101, vcc, s88, v98, s88
	s_lshl_b32 s0, s96, 7
	v_fma_f32 v102, -v99, v100, 1.0
	v_fmac_f32_e32 v100, v102, v100
	v_mul_f32_e32 v102, v101, v100
	v_fma_f32 v103, -v99, v102, v101
	v_fmac_f32_e32 v102, v103, v100
	v_fma_f32 v99, -v99, v102, v101
	v_div_fmas_f32 v99, v99, v100, v102
	v_div_fixup_f32 v98, v99, v98, s88
	s_mov_b32 s1, s15
	v_add_u32_e32 v151, -11, v0
	v_add_u32_e32 v152, -16, v0
	v_subrev_u32_e32 v153, 17, v0
	v_subrev_u32_e32 v154, 18, v0
	v_subrev_u32_e32 v155, 19, v0
	v_subrev_u32_e32 v156, 24, v0
	v_subrev_u32_e32 v157, 25, v0
	v_subrev_u32_e32 v158, 26, v0
	v_subrev_u32_e32 v159, 27, v0
	s_sub_i32 s62, s33, 31
	s_waitcnt vmcnt(0)
	v_mov_b32_e32 v100, v43
	v_mov_b32_e32 v101, v45
	v_mov_b32_e32 v102, v47
	v_mov_b32_e32 v103, v49
	v_mov_b32_e32 v43, v44
	v_mov_b32_e32 v47, v48
	v_mov_b32_e32 v44, v51
	v_mov_b32_e32 v45, v53
	v_pk_mul_f32 v[48:49], v[98:99], v[100:101] op_sel_hi:[0,1]
	v_pk_mul_f32 v[100:101], v[98:99], v[102:103] op_sel_hi:[0,1]
	v_pk_mul_f32 v[42:43], v[98:99], v[42:43] op_sel_hi:[0,1]
	v_pk_mul_f32 v[46:47], v[98:99], v[46:47] op_sel_hi:[0,1]
	v_pk_mul_f32 v[44:45], v[98:99], v[44:45] op_sel_hi:[0,1]
	v_pk_mul_f32 v[40:41], v[100:101], v[40:41]
	v_pk_mul_f32 v[6:7], v[42:43], v[6:7]
	v_pk_mul_f32 v[36:37], v[46:47], v[36:37]
	v_mov_b32_e32 v42, v57
	v_mov_b32_e32 v57, v60
	v_mov_b32_e32 v46, v55
	v_mov_b32_e32 v47, v59
	v_mov_b32_e32 v55, v58
	v_pk_mul_f32 v[8:9], v[48:49], v[8:9]
	v_mov_b32_e32 v43, v61
	v_pk_mul_f32 v[38:39], v[44:45], v[38:39]
	v_pk_mul_f32 v[44:45], v[56:57], v[40:41]
	v_pk_mul_f32 v[48:49], v[54:55], v[36:37]
	v_pk_mul_f32 v[36:37], v[46:47], v[36:37]
	v_pk_mul_f32 v[40:41], v[42:43], v[40:41]
	v_pk_fma_f32 v[42:43], v[42:43], v[8:9], v[44:45]
	v_pk_fma_f32 v[44:45], v[46:47], v[6:7], v[48:49]
	v_pk_fma_f32 v[6:7], v[54:55], v[6:7], v[36:37] neg_lo:[0,0,1] neg_hi:[0,0,1]
	v_mov_b32_e32 v36, v63
	v_mov_b32_e32 v37, v65
	v_pk_mul_f32 v[36:37], v[98:99], v[36:37] op_sel_hi:[0,1]
	v_mov_b32_e32 v51, v52
	v_pk_mul_f32 v[34:35], v[36:37], v[34:35]
	v_pk_mul_f32 v[36:37], v[98:99], v[50:51] op_sel_hi:[0,1]
	v_mov_b32_e32 v63, v64
	v_pk_mul_f32 v[36:37], v[36:37], v[2:3]
	v_pk_mul_f32 v[2:3], v[98:99], v[62:63] op_sel_hi:[0,1]
	s_waitcnt lgkmcnt(0)
	v_mov_b32_e32 v46, v81
	v_mov_b32_e32 v47, v85
	v_mov_b32_e32 v81, v84
	v_pk_fma_f32 v[8:9], v[56:57], v[8:9], v[40:41] neg_lo:[0,0,1] neg_hi:[0,0,1]
	v_pk_mul_f32 v[40:41], v[2:3], v[4:5]
	v_pk_mul_f32 v[2:3], v[80:81], v[34:35]
	v_mov_b32_e32 v48, v79
	v_mov_b32_e32 v49, v83
	v_mov_b32_e32 v79, v82
	v_pk_mul_f32 v[34:35], v[46:47], v[34:35]
	v_pk_fma_f32 v[2:3], v[46:47], v[38:39], v[2:3]
	v_pk_mul_f32 v[4:5], v[78:79], v[40:41]
	v_pk_fma_f32 v[34:35], v[80:81], v[38:39], v[34:35] neg_lo:[0,0,1] neg_hi:[0,0,1]
	v_pk_mul_f32 v[38:39], v[48:49], v[40:41]
	v_pk_fma_f32 v[4:5], v[48:49], v[36:37], v[4:5]
	v_pk_fma_f32 v[36:37], v[78:79], v[36:37], v[38:39] neg_lo:[0,0,1] neg_hi:[0,0,1]
	v_bfe_u32 v38, v35, 16, 1
	v_bfe_u32 v39, v34, 16, 1
	v_bfe_u32 v40, v9, 16, 1
	v_bfe_u32 v41, v8, 16, 1
	v_add3_u32 v41, v8, v41, s89
	v_add3_u32 v40, v9, v40, s89
	v_add3_u32 v8, v34, v39, s89
	v_add3_u32 v9, v35, v38, s89
	v_bfe_u32 v38, v36, 16, 1
	v_bfe_u32 v39, v37, 16, 1
	v_bfe_u32 v34, v6, 16, 1
	v_bfe_u32 v35, v7, 16, 1
	v_add3_u32 v37, v37, v39, s89
	v_add3_u32 v36, v36, v38, s89
	v_add3_u32 v7, v7, v35, s89
	v_add3_u32 v6, v6, v34, s89
	v_lshrrev_b32_e32 v34, 16, v36
	v_lshrrev_b32_e32 v35, 16, v37
	v_and_or_b32 v9, v9, s86, v35
	v_and_or_b32 v8, v8, s86, v34
	v_mov_b32_e32 v34, v67
	v_mov_b32_e32 v35, v69
	v_pk_mul_f32 v[34:35], v[98:99], v[34:35] op_sel_hi:[0,1]
	v_pk_mul_f32 v[32:33], v[34:35], v[32:33]
	v_mov_b32_e32 v34, v75
	v_mov_b32_e32 v35, v77
	v_pk_mul_f32 v[34:35], v[98:99], v[34:35] op_sel_hi:[0,1]
	v_mov_b32_e32 v67, v68
	v_pk_mul_f32 v[30:31], v[34:35], v[30:31]
	v_pk_mul_f32 v[34:35], v[98:99], v[66:67] op_sel_hi:[0,1]
	v_mov_b32_e32 v75, v76
	v_pk_mul_f32 v[28:29], v[34:35], v[28:29]
	v_pk_mul_f32 v[34:35], v[98:99], v[74:75] op_sel_hi:[0,1]
	v_lshrrev_b32_e32 v6, 16, v6
	v_lshrrev_b32_e32 v7, 16, v7
	v_pk_mul_f32 v[26:27], v[34:35], v[26:27]
	v_mov_b32_e32 v38, v87
	v_mov_b32_e32 v39, v91
	v_mov_b32_e32 v87, v90
	v_and_or_b32 v7, v40, s86, v7
	v_and_or_b32 v6, v41, s86, v6
	v_pk_mul_f32 v[40:41], v[86:87], v[26:27]
	v_pk_mul_f32 v[26:27], v[38:39], v[26:27]
	v_pk_fma_f32 v[40:41], v[38:39], v[28:29], v[40:41]
	v_pk_fma_f32 v[26:27], v[86:87], v[28:29], v[26:27] neg_lo:[0,0,1] neg_hi:[0,0,1]
	v_mov_b32_e32 v28, v71
	v_mov_b32_e32 v29, v73
	v_pk_mul_f32 v[28:29], v[98:99], v[28:29] op_sel_hi:[0,1]
	v_pk_mul_f32 v[24:25], v[28:29], v[24:25]
	v_mov_b32_e32 v28, v11
	v_mov_b32_e32 v29, v13
	v_pk_mul_f32 v[28:29], v[98:99], v[28:29] op_sel_hi:[0,1]
	v_mov_b32_e32 v71, v72
	v_mov_b32_e32 v34, v89
	v_mov_b32_e32 v35, v93
	v_mov_b32_e32 v89, v92
	v_pk_mul_f32 v[22:23], v[28:29], v[22:23]
	v_pk_mul_f32 v[28:29], v[98:99], v[70:71] op_sel_hi:[0,1]
	v_mov_b32_e32 v11, v12
	v_pk_mul_f32 v[36:37], v[88:89], v[30:31]
	v_pk_mul_f32 v[30:31], v[34:35], v[30:31]
	v_pk_mul_f32 v[20:21], v[28:29], v[20:21]
	v_pk_mul_f32 v[10:11], v[98:99], v[10:11] op_sel_hi:[0,1]
	v_mov_b32_e32 v28, v17
	v_mov_b32_e32 v17, v96
	v_pk_fma_f32 v[36:37], v[34:35], v[32:33], v[36:37]
	v_pk_fma_f32 v[30:31], v[88:89], v[32:33], v[30:31] neg_lo:[0,0,1] neg_hi:[0,0,1]
	v_pk_mul_f32 v[18:19], v[10:11], v[18:19]
	v_mov_b32_e32 v29, v97
	v_pk_mul_f32 v[10:11], v[16:17], v[22:23]
	v_mov_b32_e32 v32, v15
	v_mov_b32_e32 v15, v94
	v_pk_fma_f32 v[10:11], v[28:29], v[24:25], v[10:11]
	v_mov_b32_e32 v33, v95
	v_pk_mul_f32 v[12:13], v[14:15], v[18:19]
	v_bfe_u32 v34, v11, 16, 1
	v_pk_fma_f32 v[12:13], v[32:33], v[20:21], v[12:13]
	v_bfe_u32 v35, v10, 16, 1
	v_bfe_u32 v39, v36, 16, 1
	v_bfe_u32 v38, v37, 16, 1
	v_add3_u32 v36, v36, v39, s89
	v_add3_u32 v10, v10, v35, s89
	v_add3_u32 v11, v11, v34, s89
	v_bfe_u32 v34, v40, 16, 1
	v_bfe_u32 v35, v41, 16, 1
	v_bfe_u32 v39, v13, 16, 1
	v_add3_u32 v37, v37, v38, s89
	v_bfe_u32 v38, v12, 16, 1
	v_add3_u32 v13, v13, v39, s89
	v_add3_u32 v35, v41, v35, s89
	v_add3_u32 v34, v40, v34, s89
	v_add3_u32 v12, v12, v38, s89
	v_lshrrev_b32_e32 v38, 16, v34
	v_lshrrev_b32_e32 v34, 16, v35
	v_lshrrev_b32_e32 v13, 16, v13
	v_and_or_b32 v13, v11, s86, v13
	v_and_or_b32 v11, v37, s86, v34
	v_lshl_add_u64 v[34:35], v[132:133], 0, s[0:1]
	global_load_dwordx4 v[76:79], v[34:35], off
	global_load_dwordx4 v[72:75], v[34:35], off offset:1024
	global_load_dwordx4 v[68:71], v[34:35], off offset:2048
	global_load_dwordx4 v[64:67], v[34:35], off offset:3072
	v_pk_mul_f32 v[22:23], v[28:29], v[22:23]
	v_pk_mul_f32 v[18:19], v[32:33], v[18:19]
	v_pk_fma_f32 v[16:17], v[16:17], v[24:25], v[22:23] neg_lo:[0,0,1] neg_hi:[0,0,1]
	v_bfe_u32 v50, v3, 16, 1
	v_bfe_u32 v51, v2, 16, 1
	v_bfe_u32 v52, v43, 16, 1
	v_bfe_u32 v53, v42, 16, 1
	v_pk_fma_f32 v[14:15], v[14:15], v[20:21], v[18:19] neg_lo:[0,0,1] neg_hi:[0,0,1]
	v_bfe_u32 v18, v17, 16, 1
	v_bfe_u32 v19, v16, 16, 1
	v_add3_u32 v42, v42, v53, s89
	v_add3_u32 v43, v43, v52, s89
	v_add3_u32 v2, v2, v51, s89
	v_add3_u32 v3, v3, v50, s89
	v_bfe_u32 v50, v44, 16, 1
	v_bfe_u32 v51, v45, 16, 1
	v_bfe_u32 v52, v4, 16, 1
	v_bfe_u32 v53, v5, 16, 1
	v_add3_u32 v16, v16, v19, s89
	v_add3_u32 v17, v17, v18, s89
	v_bfe_u32 v18, v26, 16, 1
	v_bfe_u32 v19, v27, 16, 1
	v_bfe_u32 v22, v14, 16, 1
	v_bfe_u32 v23, v15, 16, 1
	v_add3_u32 v5, v5, v53, s89
	v_add3_u32 v4, v4, v52, s89
	v_add3_u32 v45, v45, v51, s89
	v_add3_u32 v44, v44, v50, s89
	v_bfe_u32 v20, v31, 16, 1
	v_bfe_u32 v21, v30, 16, 1
	v_add3_u32 v15, v15, v23, s89
	v_add3_u32 v14, v14, v22, s89
	v_add3_u32 v19, v27, v19, s89
	v_add3_u32 v18, v26, v18, s89
	v_lshrrev_b32_e32 v44, 16, v44
	v_lshrrev_b32_e32 v45, 16, v45
	v_lshrrev_b32_e32 v4, 16, v4
	v_lshrrev_b32_e32 v5, 16, v5
	v_lshrrev_b32_e32 v12, 16, v12
	v_add3_u32 v21, v30, v21, s89
	v_add3_u32 v20, v31, v20, s89
	v_lshrrev_b32_e32 v18, 16, v18
	v_lshrrev_b32_e32 v19, 16, v19
	v_lshrrev_b32_e32 v14, 16, v14
	v_lshrrev_b32_e32 v15, 16, v15
	v_and_or_b32 v5, v3, s86, v5
	v_and_or_b32 v4, v2, s86, v4
	v_and_or_b32 v3, v43, s86, v45
	v_and_or_b32 v2, v42, s86, v44
	v_and_or_b32 v12, v10, s86, v12
	v_and_or_b32 v10, v36, s86, v38
	v_and_or_b32 v83, v17, s86, v15
	v_and_or_b32 v82, v16, s86, v14
	v_and_or_b32 v81, v20, s86, v19
	v_and_or_b32 v80, v21, s86, v18
	v_add_u32_e32 v14, -2, v0
	v_add_u32_e32 v15, -3, v0
	v_mov_b32_e32 v32, 0
	v_mov_b32_e32 v33, v136
	v_mov_b32_e32 v34, v136
	v_mov_b32_e32 v35, v136
	v_mov_b32_e32 v36, v136
	v_mov_b32_e32 v37, v136
	v_mov_b32_e32 v38, v136
	v_mov_b32_e32 v39, v136
	v_mov_b32_e32 v40, v136
	v_mov_b32_e32 v41, v136
	v_mov_b32_e32 v42, v136
	v_mov_b32_e32 v43, v136
	v_mov_b32_e32 v44, v136
	v_mov_b32_e32 v45, v136
	v_mov_b32_e32 v46, v136
	v_mov_b32_e32 v47, v136
	v_mov_b32_e32 v16, 0
	v_mov_b32_e32 v17, v136
	v_mov_b32_e32 v18, v136
	v_mov_b32_e32 v19, v136
	v_mov_b32_e32 v20, v136
	v_mov_b32_e32 v21, v136
	v_mov_b32_e32 v22, v136
	v_mov_b32_e32 v23, v136
	v_mov_b32_e32 v24, v136
	v_mov_b32_e32 v25, v136
	v_mov_b32_e32 v26, v136
	v_mov_b32_e32 v27, v136
	v_mov_b32_e32 v28, v136
	v_mov_b32_e32 v29, v136
	v_mov_b32_e32 v30, v136
	v_mov_b32_e32 v31, v136
	s_branch .LBB0_1504

.LBB0_1525:
	s_or_b32 s0, s2, s82
	s_lshl_b32 s2, s0, 5
	v_or_b32_e32 v0, s2, v172
	v_lshl_add_u32 v149, v0, 2, s26
	v_add_u32_e32 v0, s73, v149
	v_lshl_add_u64 v[2:3], s[56:57], 0, v[0:1]
	v_mov_b64_e32 v[4:5], s[12:13]
	v_mad_u64_u32 v[4:5], s[0:1], v2, s27, v[4:5]
	v_mad_i32_i24 v5, v3, s27, v5
	v_lshl_add_u64 v[2:3], v[4:5], 0, s[14:15]
	v_mov_b32_e32 v129, v1
	v_lshl_add_u64 v[6:7], v[2:3], 0, v[128:129]
	v_add_co_u32_e32 v2, vcc, s83, v6
	s_mov_b64 s[0:1], 0xd000c00
	s_nop 0
	v_addc_co_u32_e32 v3, vcc, 0, v7, vcc
	global_load_dwordx4 v[2:5], v[2:3], off offset:3072
	v_lshl_add_u64 v[14:15], v[6:7], 0, s[0:1]
	global_load_dwordx4 v[6:9], v[14:15], off offset:64
	global_load_dwordx4 v[10:13], v[14:15], off offset:32
	s_nop 0
	global_load_dwordx4 v[14:17], v[14:15], off offset:96
	v_lshlrev_b64 v[244:245], 8, v[0:1]
	v_lshl_add_u64 v[246:247], v[118:119], 0, v[244:245]
	global_load_dwordx4 v[174:177], v[120:121], off offset:320
	global_load_dwordx4 v[178:181], v[120:121], off offset:448
	global_load_dwordx4 v[182:185], v[120:121], off offset:336
	global_load_dwordx4 v[186:189], v[246:247], off offset:128
	global_load_dwordx4 v[190:193], v[246:247], off offset:144
	global_load_dwordx4 v[194:197], v[120:121], off offset:464
	global_load_dwordx4 v[198:201], v[120:121], off offset:256
	global_load_dwordx4 v[202:205], v[120:121], off offset:272
	global_load_dwordx4 v[206:209], v[120:121], off offset:384
	global_load_dwordx4 v[210:213], v[120:121], off offset:400
	global_load_dwordx4 v[214:217], v[246:247], off offset:160
	global_load_dwordx4 v[218:221], v[246:247], off offset:176
	global_load_dwordx4 v[222:225], v[246:247], off
	global_load_dwordx4 v[232:235], v[246:247], off offset:16
	global_load_dwordx4 v[236:239], v[246:247], off offset:32
	global_load_dwordx4 v[240:243], v[246:247], off offset:48
	s_or_b32 s33, s2, s74
	s_max_i32 s2, s33, 0x80
	s_add_i32 s71, s2, 0xffffff80
	s_cmp_gt_i32 s71, s33
	s_waitcnt vmcnt(18)
	v_lshlrev_b32_e32 v27, 16, v7
	v_lshlrev_b32_e32 v29, 16, v3
	v_lshlrev_b32_e32 v28, 16, v2
	v_and_b32_e32 v33, 0xffff0000, v3
	v_and_b32_e32 v32, 0xffff0000, v2
	v_lshlrev_b32_e32 v26, 16, v6
	v_and_b32_e32 v31, 0xffff0000, v7
	v_and_b32_e32 v30, 0xffff0000, v6
	v_lshlrev_b32_e32 v19, 16, v9
	v_lshlrev_b32_e32 v18, 16, v8
	v_and_b32_e32 v23, 0xffff0000, v9
	v_and_b32_e32 v22, 0xffff0000, v8
	s_waitcnt vmcnt(17)
	v_lshlrev_b32_e32 v7, 16, v11
	v_lshlrev_b32_e32 v6, 16, v10
	v_and_b32_e32 v9, 0xffff0000, v11
	v_and_b32_e32 v8, 0xffff0000, v10
	v_lshlrev_b32_e32 v3, 16, v13
	v_lshlrev_b32_e32 v2, 16, v12
	v_and_b32_e32 v39, 0xffff0000, v13
	v_and_b32_e32 v38, 0xffff0000, v12
	v_pk_mul_f32 v[10:11], v[28:29], v[28:29]
	v_pk_mul_f32 v[12:13], v[32:33], v[32:33]
	v_lshlrev_b32_e32 v21, 16, v5
	v_add_f32_e32 v10, v10, v12
	v_lshlrev_b32_e32 v20, 16, v4
	v_add_f32_e32 v10, v11, v10
	v_and_b32_e32 v25, 0xffff0000, v5
	v_and_b32_e32 v24, 0xffff0000, v4
	s_waitcnt vmcnt(16)
	v_lshlrev_b32_e32 v37, 16, v15
	v_lshlrev_b32_e32 v36, 16, v14
	v_and_b32_e32 v41, 0xffff0000, v15
	v_and_b32_e32 v40, 0xffff0000, v14
	v_pk_mul_f32 v[14:15], v[20:21], v[20:21]
	v_add_f32_e32 v10, v13, v10
	v_lshlrev_b32_e32 v5, 16, v17
	v_lshlrev_b32_e32 v4, 16, v16
	v_and_b32_e32 v35, 0xffff0000, v17
	v_and_b32_e32 v34, 0xffff0000, v16
	v_pk_mul_f32 v[16:17], v[24:25], v[24:25]
	v_add_f32_e32 v10, v14, v10
	v_add_f32_e32 v10, v16, v10
	v_add_f32_e32 v10, v15, v10
	v_pk_mul_f32 v[42:43], v[6:7], v[6:7]
	v_add_f32_e32 v10, v17, v10
	v_pk_mul_f32 v[44:45], v[8:9], v[8:9]
	v_add_f32_e32 v10, v42, v10
	v_add_f32_e32 v10, v44, v10
	v_add_f32_e32 v10, v43, v10
	v_pk_mul_f32 v[46:47], v[2:3], v[2:3]
	v_add_f32_e32 v10, v45, v10
	v_pk_mul_f32 v[48:49], v[38:39], v[38:39]
	v_add_f32_e32 v10, v46, v10
	v_add_f32_e32 v10, v48, v10
	v_add_f32_e32 v10, v47, v10
	v_pk_mul_f32 v[50:51], v[26:27], v[26:27]
	v_add_f32_e32 v10, v49, v10
	v_pk_mul_f32 v[52:53], v[30:31], v[30:31]
	v_add_f32_e32 v10, v50, v10
	v_add_f32_e32 v10, v52, v10
	v_add_f32_e32 v10, v51, v10
	v_pk_mul_f32 v[54:55], v[18:19], v[18:19]
	v_add_f32_e32 v10, v53, v10
	v_pk_mul_f32 v[56:57], v[22:23], v[22:23]
	v_add_f32_e32 v10, v54, v10
	v_add_f32_e32 v10, v56, v10
	v_add_f32_e32 v10, v55, v10
	v_pk_mul_f32 v[58:59], v[36:37], v[36:37]
	v_add_f32_e32 v10, v57, v10
	v_pk_mul_f32 v[60:61], v[40:41], v[40:41]
	v_add_f32_e32 v10, v58, v10
	v_add_f32_e32 v10, v60, v10
	v_add_f32_e32 v10, v59, v10
	v_pk_mul_f32 v[62:63], v[4:5], v[4:5]
	v_add_f32_e32 v10, v61, v10
	v_pk_mul_f32 v[64:65], v[34:35], v[34:35]
	v_add_f32_e32 v10, v62, v10
	v_add_f32_e32 v10, v64, v10
	v_add_f32_e32 v10, v63, v10
	v_add_f32_e32 v10, v65, v10
	ds_bpermute_b32 v11, v117, v10
	s_cbranch_scc1 .LBB0_1544
	s_waitcnt vmcnt(0)
	v_mov_b32_e32 v42, v174
	v_mov_b32_e32 v43, v175
	v_mov_b32_e32 v44, v176
	v_mov_b32_e32 v45, v177
	v_mov_b32_e32 v46, v178
	v_mov_b32_e32 v47, v179
	v_mov_b32_e32 v48, v180
	v_mov_b32_e32 v49, v181
	v_mov_b32_e32 v50, v182
	v_mov_b32_e32 v51, v183
	v_mov_b32_e32 v52, v184
	v_mov_b32_e32 v53, v185
	v_lshlrev_b64 v[12:13], 8, v[0:1]
	v_lshl_add_u64 v[94:95], v[118:119], 0, v[12:13]
	v_mov_b32_e32 v54, v186
	v_mov_b32_e32 v55, v187
	v_mov_b32_e32 v56, v188
	v_mov_b32_e32 v57, v189
	v_mov_b32_e32 v58, v190
	v_mov_b32_e32 v59, v191
	v_mov_b32_e32 v60, v192
	v_mov_b32_e32 v61, v193
	v_mov_b32_e32 v62, v194
	v_mov_b32_e32 v63, v195
	v_mov_b32_e32 v64, v196
	v_mov_b32_e32 v65, v197
	s_waitcnt lgkmcnt(0)
	v_add_f32_e32 v14, v10, v11
	v_mov_b32_e32 v66, v198
	v_mov_b32_e32 v67, v199
	v_mov_b32_e32 v68, v200
	v_mov_b32_e32 v69, v201
	v_mov_b32_e32 v70, v202
	v_mov_b32_e32 v71, v203
	v_mov_b32_e32 v72, v204
	v_mov_b32_e32 v73, v205
	v_mov_b32_e32 v74, v206
	v_mov_b32_e32 v75, v207
	v_mov_b32_e32 v76, v208
	v_mov_b32_e32 v77, v209
	v_mov_b32_e32 v10, v210
	v_mov_b32_e32 v11, v211
	v_mov_b32_e32 v12, v212
	v_mov_b32_e32 v13, v213
	v_mov_b32_e32 v78, v214
	v_mov_b32_e32 v79, v215
	v_mov_b32_e32 v80, v216
	v_mov_b32_e32 v81, v217
	v_mov_b32_e32 v82, v218
	v_mov_b32_e32 v83, v219
	v_mov_b32_e32 v84, v220
	v_mov_b32_e32 v85, v221
	v_fmamk_f32 v14, v14, 0x3c800000, v141
	v_mul_f32_e32 v15, 0x4f800000, v14
	v_cmp_gt_f32_e32 vcc, s87, v14
	v_mov_b32_e32 v86, v222
	v_mov_b32_e32 v87, v223
	v_mov_b32_e32 v88, v224
	v_mov_b32_e32 v89, v225
	v_mov_b32_e32 v90, v232
	v_mov_b32_e32 v91, v233
	v_mov_b32_e32 v92, v234
	v_mov_b32_e32 v93, v235
	v_cndmask_b32_e32 v14, v14, v15, vcc
	v_sqrt_f32_e32 v15, v14
	v_or_b32_e32 v0, s33, v172
	v_mov_b32_e32 v129, 0
	v_sub_u32_e32 v0, v0, v123
	v_add_u32_e32 v16, -1, v15
	v_add_u32_e32 v17, 1, v15
	v_fma_f32 v96, -v16, v15, v14
	v_fma_f32 v97, -v17, v15, v14
	v_cmp_ge_f32_e64 s[0:1], 0, v96
	s_add_i32 s3, s2, 0xffffffa0
	s_lshl_b32 s66, s71, 6
	v_cndmask_b32_e64 v15, v15, v16, s[0:1]
	v_cmp_lt_f32_e64 s[0:1], 0, v97
	s_add_i32 s62, s33, 0xffffffa0
	v_add_u32_e32 v150, -8, v0
	v_cndmask_b32_e64 v15, v15, v17, s[0:1]
	v_mul_f32_e32 v16, 0x37800000, v15
	v_cndmask_b32_e32 v15, v15, v16, vcc
	v_cmp_class_f32_e32 vcc, v14, v142
	v_add_u32_e32 v151, -9, v0
	v_add_u32_e32 v152, -10, v0
	v_cndmask_b32_e32 v98, v15, v14, vcc
	v_mov_b32_e32 v14, v236
	v_mov_b32_e32 v15, v237
	v_mov_b32_e32 v16, v238
	v_mov_b32_e32 v17, v239
	s_nop 0
	v_mov_b32_e32 v94, v240
	v_mov_b32_e32 v95, v241
	v_mov_b32_e32 v96, v242
	v_mov_b32_e32 v97, v243
	v_div_scale_f32 v99, s[0:1], v98, v98, s88
	v_rcp_f32_e32 v100, v99
	v_div_scale_f32 v101, vcc, s88, v98, s88
	s_lshl_b32 s0, s71, 7
	v_fma_f32 v102, -v99, v100, 1.0
	v_fmac_f32_e32 v100, v102, v100
	v_mul_f32_e32 v102, v101, v100
	v_fma_f32 v103, -v99, v102, v101
	v_fmac_f32_e32 v102, v103, v100
	v_fma_f32 v99, -v99, v102, v101
	v_div_fmas_f32 v99, v99, v100, v102
	v_div_fixup_f32 v98, v99, v98, s88
	s_mov_b32 s1, s15
	v_add_u32_e32 v153, -11, v0
	v_add_u32_e32 v154, -16, v0
	v_subrev_u32_e32 v155, 17, v0
	v_subrev_u32_e32 v156, 18, v0
	v_subrev_u32_e32 v157, 19, v0
	v_subrev_u32_e32 v158, 24, v0
	v_subrev_u32_e32 v159, 25, v0
	v_subrev_u32_e32 v160, 26, v0
	v_subrev_u32_e32 v161, 27, v0
	s_sub_i32 s63, s33, 31
	s_waitcnt vmcnt(0)
	v_mov_b32_e32 v100, v43
	v_mov_b32_e32 v101, v45
	v_mov_b32_e32 v102, v47
	v_mov_b32_e32 v103, v49
	v_mov_b32_e32 v43, v44
	v_mov_b32_e32 v47, v48
	v_mov_b32_e32 v44, v51
	v_mov_b32_e32 v45, v53
	v_pk_mul_f32 v[48:49], v[98:99], v[100:101] op_sel_hi:[0,1]
	v_pk_mul_f32 v[100:101], v[98:99], v[102:103] op_sel_hi:[0,1]
	v_pk_mul_f32 v[42:43], v[98:99], v[42:43] op_sel_hi:[0,1]
	v_pk_mul_f32 v[46:47], v[98:99], v[46:47] op_sel_hi:[0,1]
	v_pk_mul_f32 v[44:45], v[98:99], v[44:45] op_sel_hi:[0,1]
	v_pk_mul_f32 v[40:41], v[100:101], v[40:41]
	v_pk_mul_f32 v[6:7], v[42:43], v[6:7]
	v_pk_mul_f32 v[36:37], v[46:47], v[36:37]
	v_mov_b32_e32 v42, v57
	v_mov_b32_e32 v57, v60
	v_mov_b32_e32 v46, v55
	v_mov_b32_e32 v47, v59
	v_mov_b32_e32 v55, v58
	v_pk_mul_f32 v[8:9], v[48:49], v[8:9]
	v_mov_b32_e32 v43, v61
	v_pk_mul_f32 v[38:39], v[44:45], v[38:39]
	v_pk_mul_f32 v[44:45], v[56:57], v[40:41]
	v_pk_mul_f32 v[48:49], v[54:55], v[36:37]
	v_pk_mul_f32 v[36:37], v[46:47], v[36:37]
	v_pk_mul_f32 v[40:41], v[42:43], v[40:41]
	v_pk_fma_f32 v[42:43], v[42:43], v[8:9], v[44:45]
	v_pk_fma_f32 v[44:45], v[46:47], v[6:7], v[48:49]
	v_pk_fma_f32 v[6:7], v[54:55], v[6:7], v[36:37] neg_lo:[0,0,1] neg_hi:[0,0,1]
	v_mov_b32_e32 v36, v63
	v_mov_b32_e32 v37, v65
	v_pk_mul_f32 v[36:37], v[98:99], v[36:37] op_sel_hi:[0,1]
	v_mov_b32_e32 v51, v52
	v_pk_mul_f32 v[34:35], v[36:37], v[34:35]
	v_pk_mul_f32 v[36:37], v[98:99], v[50:51] op_sel_hi:[0,1]
	v_mov_b32_e32 v63, v64
	v_pk_mul_f32 v[36:37], v[36:37], v[2:3]
	v_pk_mul_f32 v[2:3], v[98:99], v[62:63] op_sel_hi:[0,1]
	s_waitcnt lgkmcnt(0)
	v_mov_b32_e32 v46, v81
	v_mov_b32_e32 v47, v85
	v_mov_b32_e32 v81, v84
	v_pk_fma_f32 v[8:9], v[56:57], v[8:9], v[40:41] neg_lo:[0,0,1] neg_hi:[0,0,1]
	v_pk_mul_f32 v[40:41], v[2:3], v[4:5]
	v_pk_mul_f32 v[2:3], v[80:81], v[34:35]
	v_mov_b32_e32 v48, v79
	v_mov_b32_e32 v49, v83
	v_mov_b32_e32 v79, v82
	v_pk_mul_f32 v[34:35], v[46:47], v[34:35]
	v_pk_fma_f32 v[2:3], v[46:47], v[38:39], v[2:3]
	v_pk_mul_f32 v[4:5], v[78:79], v[40:41]
	v_pk_fma_f32 v[34:35], v[80:81], v[38:39], v[34:35] neg_lo:[0,0,1] neg_hi:[0,0,1]
	v_pk_mul_f32 v[38:39], v[48:49], v[40:41]
	v_pk_fma_f32 v[4:5], v[48:49], v[36:37], v[4:5]
	v_pk_fma_f32 v[36:37], v[78:79], v[36:37], v[38:39] neg_lo:[0,0,1] neg_hi:[0,0,1]
	v_bfe_u32 v38, v35, 16, 1
	v_bfe_u32 v39, v34, 16, 1
	v_bfe_u32 v40, v9, 16, 1
	v_bfe_u32 v41, v8, 16, 1
	v_add3_u32 v41, v8, v41, s89
	v_add3_u32 v40, v9, v40, s89
	v_add3_u32 v8, v34, v39, s89
	v_add3_u32 v9, v35, v38, s89
	v_bfe_u32 v38, v36, 16, 1
	v_bfe_u32 v39, v37, 16, 1
	v_bfe_u32 v34, v6, 16, 1
	v_bfe_u32 v35, v7, 16, 1
	v_add3_u32 v37, v37, v39, s89
	v_add3_u32 v36, v36, v38, s89
	v_add3_u32 v7, v7, v35, s89
	v_add3_u32 v6, v6, v34, s89
	v_lshrrev_b32_e32 v34, 16, v36
	v_lshrrev_b32_e32 v35, 16, v37
	v_and_or_b32 v9, v9, s86, v35
	v_and_or_b32 v8, v8, s86, v34
	v_mov_b32_e32 v34, v67
	v_mov_b32_e32 v35, v69
	v_pk_mul_f32 v[34:35], v[98:99], v[34:35] op_sel_hi:[0,1]
	v_pk_mul_f32 v[32:33], v[34:35], v[32:33]
	v_mov_b32_e32 v34, v75
	v_mov_b32_e32 v35, v77
	v_pk_mul_f32 v[34:35], v[98:99], v[34:35] op_sel_hi:[0,1]
	v_mov_b32_e32 v67, v68
	v_pk_mul_f32 v[30:31], v[34:35], v[30:31]
	v_pk_mul_f32 v[34:35], v[98:99], v[66:67] op_sel_hi:[0,1]
	v_mov_b32_e32 v75, v76
	v_pk_mul_f32 v[28:29], v[34:35], v[28:29]
	v_pk_mul_f32 v[34:35], v[98:99], v[74:75] op_sel_hi:[0,1]
	v_lshrrev_b32_e32 v6, 16, v6
	v_lshrrev_b32_e32 v7, 16, v7
	v_pk_mul_f32 v[26:27], v[34:35], v[26:27]
	v_mov_b32_e32 v38, v87
	v_mov_b32_e32 v39, v91
	v_mov_b32_e32 v87, v90
	v_and_or_b32 v7, v40, s86, v7
	v_and_or_b32 v6, v41, s86, v6
	v_pk_mul_f32 v[40:41], v[86:87], v[26:27]
	v_pk_mul_f32 v[26:27], v[38:39], v[26:27]
	v_pk_fma_f32 v[40:41], v[38:39], v[28:29], v[40:41]
	v_pk_fma_f32 v[26:27], v[86:87], v[28:29], v[26:27] neg_lo:[0,0,1] neg_hi:[0,0,1]
	v_mov_b32_e32 v28, v71
	v_mov_b32_e32 v29, v73
	v_pk_mul_f32 v[28:29], v[98:99], v[28:29] op_sel_hi:[0,1]
	v_pk_mul_f32 v[24:25], v[28:29], v[24:25]
	v_mov_b32_e32 v28, v11
	v_mov_b32_e32 v29, v13
	v_pk_mul_f32 v[28:29], v[98:99], v[28:29] op_sel_hi:[0,1]
	v_mov_b32_e32 v71, v72
	v_mov_b32_e32 v34, v89
	v_mov_b32_e32 v35, v93
	v_mov_b32_e32 v89, v92
	v_pk_mul_f32 v[22:23], v[28:29], v[22:23]
	v_pk_mul_f32 v[28:29], v[98:99], v[70:71] op_sel_hi:[0,1]
	v_mov_b32_e32 v11, v12
	v_pk_mul_f32 v[36:37], v[88:89], v[30:31]
	v_pk_mul_f32 v[30:31], v[34:35], v[30:31]
	v_pk_mul_f32 v[20:21], v[28:29], v[20:21]
	v_pk_mul_f32 v[10:11], v[98:99], v[10:11] op_sel_hi:[0,1]
	v_mov_b32_e32 v28, v17
	v_mov_b32_e32 v17, v96
	v_pk_fma_f32 v[36:37], v[34:35], v[32:33], v[36:37]
	v_pk_fma_f32 v[30:31], v[88:89], v[32:33], v[30:31] neg_lo:[0,0,1] neg_hi:[0,0,1]
	v_pk_mul_f32 v[18:19], v[10:11], v[18:19]
	v_mov_b32_e32 v29, v97
	v_pk_mul_f32 v[10:11], v[16:17], v[22:23]
	v_mov_b32_e32 v32, v15
	v_mov_b32_e32 v15, v94
	v_pk_fma_f32 v[10:11], v[28:29], v[24:25], v[10:11]
	v_mov_b32_e32 v33, v95
	v_pk_mul_f32 v[12:13], v[14:15], v[18:19]
	v_bfe_u32 v34, v11, 16, 1
	v_pk_fma_f32 v[12:13], v[32:33], v[20:21], v[12:13]
	v_bfe_u32 v35, v10, 16, 1
	v_bfe_u32 v39, v36, 16, 1
	v_bfe_u32 v38, v37, 16, 1
	v_add3_u32 v36, v36, v39, s89
	v_add3_u32 v10, v10, v35, s89
	v_add3_u32 v11, v11, v34, s89
	v_bfe_u32 v34, v40, 16, 1
	v_bfe_u32 v35, v41, 16, 1
	v_bfe_u32 v39, v13, 16, 1
	v_add3_u32 v37, v37, v38, s89
	v_bfe_u32 v38, v12, 16, 1
	v_add3_u32 v13, v13, v39, s89
	v_add3_u32 v35, v41, v35, s89
	v_add3_u32 v34, v40, v34, s89
	v_add3_u32 v12, v12, v38, s89
	v_lshrrev_b32_e32 v38, 16, v34
	v_lshrrev_b32_e32 v34, 16, v35
	v_lshrrev_b32_e32 v13, 16, v13
	v_and_or_b32 v13, v11, s86, v13
	v_and_or_b32 v11, v37, s86, v34
	v_lshl_add_u64 v[34:35], v[134:135], 0, s[0:1]
	global_load_dwordx4 v[76:79], v[34:35], off
	global_load_dwordx4 v[72:75], v[34:35], off offset:1024
	global_load_dwordx4 v[68:71], v[34:35], off offset:2048
	global_load_dwordx4 v[64:67], v[34:35], off offset:3072
	v_pk_mul_f32 v[22:23], v[28:29], v[22:23]
	v_pk_mul_f32 v[18:19], v[32:33], v[18:19]
	v_pk_fma_f32 v[16:17], v[16:17], v[24:25], v[22:23] neg_lo:[0,0,1] neg_hi:[0,0,1]
	v_bfe_u32 v50, v3, 16, 1
	v_bfe_u32 v51, v2, 16, 1
	v_bfe_u32 v52, v43, 16, 1
	v_bfe_u32 v53, v42, 16, 1
	v_pk_fma_f32 v[14:15], v[14:15], v[20:21], v[18:19] neg_lo:[0,0,1] neg_hi:[0,0,1]
	v_bfe_u32 v18, v17, 16, 1
	v_bfe_u32 v19, v16, 16, 1
	v_add3_u32 v42, v42, v53, s89
	v_add3_u32 v43, v43, v52, s89
	v_add3_u32 v2, v2, v51, s89
	v_add3_u32 v3, v3, v50, s89
	v_bfe_u32 v50, v44, 16, 1
	v_bfe_u32 v51, v45, 16, 1
	v_bfe_u32 v52, v4, 16, 1
	v_bfe_u32 v53, v5, 16, 1
	v_add3_u32 v16, v16, v19, s89
	v_add3_u32 v17, v17, v18, s89
	v_bfe_u32 v18, v26, 16, 1
	v_bfe_u32 v19, v27, 16, 1
	v_bfe_u32 v22, v14, 16, 1
	v_bfe_u32 v23, v15, 16, 1
	v_add3_u32 v5, v5, v53, s89
	v_add3_u32 v4, v4, v52, s89
	v_add3_u32 v45, v45, v51, s89
	v_add3_u32 v44, v44, v50, s89
	v_bfe_u32 v20, v31, 16, 1
	v_bfe_u32 v21, v30, 16, 1
	v_add3_u32 v15, v15, v23, s89
	v_add3_u32 v14, v14, v22, s89
	v_add3_u32 v19, v27, v19, s89
	v_add3_u32 v18, v26, v18, s89
	v_lshrrev_b32_e32 v44, 16, v44
	v_lshrrev_b32_e32 v45, 16, v45
	v_lshrrev_b32_e32 v4, 16, v4
	v_lshrrev_b32_e32 v5, 16, v5
	v_lshrrev_b32_e32 v12, 16, v12
	v_add3_u32 v21, v30, v21, s89
	v_add3_u32 v20, v31, v20, s89
	v_lshrrev_b32_e32 v18, 16, v18
	v_lshrrev_b32_e32 v19, 16, v19
	v_lshrrev_b32_e32 v14, 16, v14
	v_lshrrev_b32_e32 v15, 16, v15
	v_and_or_b32 v5, v3, s86, v5
	v_and_or_b32 v4, v2, s86, v4
	v_and_or_b32 v3, v43, s86, v45
	v_and_or_b32 v2, v42, s86, v44
	v_and_or_b32 v12, v10, s86, v12
	v_and_or_b32 v10, v36, s86, v38
	v_and_or_b32 v83, v17, s86, v15
	v_and_or_b32 v82, v16, s86, v14
	v_and_or_b32 v81, v20, s86, v19
	v_and_or_b32 v80, v21, s86, v18
	v_add_u32_e32 v14, -2, v0
	v_add_u32_e32 v15, -3, v0
	v_mov_b32_e32 v32, 0
	v_mov_b32_e32 v33, v129
	v_mov_b32_e32 v34, v129
	v_mov_b32_e32 v35, v129
	v_mov_b32_e32 v36, v129
	v_mov_b32_e32 v37, v129
	v_mov_b32_e32 v38, v129
	v_mov_b32_e32 v39, v129
	v_mov_b32_e32 v40, v129
	v_mov_b32_e32 v41, v129
	v_mov_b32_e32 v42, v129
	v_mov_b32_e32 v43, v129
	v_mov_b32_e32 v44, v129
	v_mov_b32_e32 v45, v129
	v_mov_b32_e32 v46, v129
	v_mov_b32_e32 v47, v129
	v_mov_b32_e32 v16, 0
	v_mov_b32_e32 v17, v129
	v_mov_b32_e32 v18, v129
	v_mov_b32_e32 v19, v129
	v_mov_b32_e32 v20, v129
	v_mov_b32_e32 v21, v129
	v_mov_b32_e32 v22, v129
	v_mov_b32_e32 v23, v129
	v_mov_b32_e32 v24, v129
	v_mov_b32_e32 v25, v129
	v_mov_b32_e32 v26, v129
	v_mov_b32_e32 v27, v129
	v_mov_b32_e32 v28, v129
	v_mov_b32_e32 v29, v129
	v_mov_b32_e32 v30, v129
	v_mov_b32_e32 v31, v129
	s_branch .LBB0_1528
